# NA attention QK^T: the 8 K-fragment LDS reads per tile issued together into 8 dead register quads with counted waits (was read->wait->mfma x8 on one quad)
# speedup vs baseline: 1.0066x; 1.0066x over previous
.LBB0_861:
	s_add_i32 s0, s97, -4
	s_cmp_lt_i32 s0, s6
	s_cselect_b64 s[2:3], -1, 0
	s_add_i32 s43, s7, s97
	s_add_i32 s0, s43, -4
	v_cmp_lt_u32_e32 vcc, s0, v147
	v_cmp_ge_u32_e64 s[0:1], s0, v148
	s_or_b64 s[0:1], vcc, s[0:1]
	v_cndmask_b32_e64 v0, 0, 1, s[2:3]
	s_and_b64 s[0:1], s[2:3], s[0:1]
	s_xor_b64 s[2:3], s[0:1], -1
	v_cmp_ne_u32_e64 s[46:47], 1, v0
	s_and_saveexec_b64 s[0:1], s[2:3]
	s_cbranch_execz .LBB0_930
	v_add_u32_e32 v0, v149, v150
	v_add_u32_e32 v6, v149, v151
	v_add_u32_e32 v7, v149, v152
	v_add_u32_e32 v8, v149, v153
	ds_read_b128 v[2:5], v0
	ds_read_b128 v[10:13], v6
	ds_read_b128 v[182:185], v7
	ds_read_b128 v[186:189], v8
	ds_read_b128 v[190:193], v0 offset:4096
	ds_read_b128 v[194:197], v6 offset:4096
	ds_read_b128 v[198:201], v7 offset:4096
	ds_read_b128 v[202:205], v8 offset:4096
	s_and_b64 vcc, exec, s[46:47]
	s_waitcnt lgkmcnt(7)
	s_nop 0
	v_mfma_f32_32x32x16_bf16 v[64:79], v[2:5], v[80:83], 0
	s_waitcnt lgkmcnt(6)
	s_nop 0
	v_mfma_f32_32x32x16_bf16 v[64:79], v[10:13], v[84:87], v[64:79]
	s_waitcnt lgkmcnt(5)
	s_nop 0
	v_mfma_f32_32x32x16_bf16 v[64:79], v[182:185], v[88:91], v[64:79]
	s_waitcnt lgkmcnt(4)
	s_nop 0
	v_mfma_f32_32x32x16_bf16 v[64:79], v[186:189], v[92:95], v[64:79]
	s_waitcnt lgkmcnt(3)
	s_nop 0
	v_mfma_f32_32x32x16_bf16 v[48:63], v[190:193], v[80:83], 0
	s_waitcnt lgkmcnt(2)
	s_nop 0
	v_mfma_f32_32x32x16_bf16 v[48:63], v[194:197], v[84:87], v[48:63]
	s_waitcnt lgkmcnt(1)
	s_nop 0
	v_mfma_f32_32x32x16_bf16 v[48:63], v[198:201], v[88:91], v[48:63]
	s_waitcnt lgkmcnt(0)
	s_nop 0
	v_mfma_f32_32x32x16_bf16 v[48:63], v[202:205], v[92:95], v[48:63]
	s_cbranch_vccnz .LBB0_928
	v_mov_b32_e32 v2, 0xff800000
	v_mov_b32_e32 v3, 0xff800000
	s_and_saveexec_b64 s[2:3], s[54:55]
	s_cbranch_execz .LBB0_865
	v_add_u32_e32 v0, v156, v155
	ds_read_b32 v0, v0 offset:34720
	s_waitcnt lgkmcnt(0)
	v_add_f32_e32 v3, v64, v0

.LBB0_946:
	s_cmp_lt_i32 s48, s6
	s_cselect_b64 s[2:3], -1, 0
	s_add_i32 s43, s43, -3
	v_cmp_lt_u32_e32 vcc, s43, v147
	v_cmp_ge_u32_e64 s[0:1], s43, v148
	s_or_b64 s[0:1], vcc, s[0:1]
	s_and_b64 s[0:1], s[2:3], s[0:1]
	s_xor_b64 s[4:5], s[0:1], -1
	s_and_saveexec_b64 s[0:1], s[4:5]
	s_cbranch_execz .LBB0_1015
	v_add_u32_e32 v6, v149, v150
	v_add_u32_e32 v7, v149, v151
	v_add_u32_e32 v8, v149, v152
	v_add_u32_e32 v9, v149, v153
	ds_read_b128 v[2:5], v6 offset:8192
	ds_read_b128 v[10:13], v7 offset:8192
	ds_read_b128 v[182:185], v8 offset:8192
	ds_read_b128 v[186:189], v9 offset:8192
	ds_read_b128 v[190:193], v6 offset:12288
	ds_read_b128 v[194:197], v7 offset:12288
	ds_read_b128 v[198:201], v8 offset:12288
	ds_read_b128 v[202:205], v9 offset:12288
	s_andn2_b64 vcc, exec, s[2:3]
	s_waitcnt lgkmcnt(7)
	s_nop 0
	v_mfma_f32_32x32x16_bf16 v[64:79], v[2:5], v[80:83], 0
	s_waitcnt lgkmcnt(6)
	s_nop 0
	v_mfma_f32_32x32x16_bf16 v[64:79], v[10:13], v[84:87], v[64:79]
	s_waitcnt lgkmcnt(5)
	s_nop 0
	v_mfma_f32_32x32x16_bf16 v[64:79], v[182:185], v[88:91], v[64:79]
	s_waitcnt lgkmcnt(4)
	s_nop 0
	v_mfma_f32_32x32x16_bf16 v[64:79], v[186:189], v[92:95], v[64:79]
	s_waitcnt lgkmcnt(3)
	s_nop 0
	v_mfma_f32_32x32x16_bf16 v[48:63], v[190:193], v[80:83], 0
	s_waitcnt lgkmcnt(2)
	s_nop 0
	v_mfma_f32_32x32x16_bf16 v[48:63], v[194:197], v[84:87], v[48:63]
	s_waitcnt lgkmcnt(1)
	s_nop 0
	v_mfma_f32_32x32x16_bf16 v[48:63], v[198:201], v[88:91], v[48:63]
	s_waitcnt lgkmcnt(0)
	s_nop 0
	v_mfma_f32_32x32x16_bf16 v[48:63], v[202:205], v[92:95], v[48:63]
	s_cbranch_vccnz .LBB0_1013
	v_mov_b32_e32 v3, 0xff800000
	v_add_u32_e32 v2, v156, v155
	v_mov_b32_e32 v4, 0xff800000
	s_and_saveexec_b64 s[2:3], s[54:55]
	s_cbranch_execz .LBB0_950
	ds_read_b32 v4, v2 offset:34844
	s_waitcnt lgkmcnt(0)
	v_add_f32_e32 v4, v64, v4
